# P0 adaLN gemv main loop rewritten: weight-row loads double-buffered (next batch in flight during the FMAs)
# speedup vs baseline: 1.0058x; 1.0028x over previous
; __device__ __forceinline__ float fast_sigmoid(float x) { return __builtin_amdgcn_rcpf(1.0f + __builtin_amdgcn_exp2f(-x * LOG2E)); }
; template <bool SILU>
; __device__ __forceinline__ void gemv9_unit(const Ctx& X, const float* c0, int cstride, const float* c8, const float* W, int ldw, int j0, const float* bias, float* out, int ostride) {
;     ...
;     __syncthreads();
;     for (int i = X.tid; i < 9 * 1024; i += 512) { const int r = i >> 10, k = i & 1023; float v = r < 8 ? c0[(size_t)r * cstride + k] : c8[k]; if (SILU) v = v * fast_sigmoid(v); sc[i] = v; }
;     __syncthreads();
;     const int cgi = X.tid & 15, kg = X.tid >> 4;
;     const float* wp = W + (size_t)(kg * 32) * ldw + j0 + cgi * 4;
;     f32x4 a[9];
; #pragma unroll
;     for (int r = 0; r < 9; ++r) a[r] = (f32x4){0.f, 0.f, 0.f, 0.f};
; __global__ void __launch_bounds__(512, 2) fwd_megakernel(Args args) {
;     ...
;         for (int u = X.bx; u < 288; u += GW) { const int l = u / 144, j0 = (u % 144) * 64; gemv9_unit<true>(X, args.in[1], 1024, args.in[3], args.in[4] + (size_t)l * 1024 * 9216, 9216, j0, args.in[5] + (size_t)l * 9216, MOD + (size_t)l * 9 * 9216, 9216); }
.LBB0_36:
	s_barrier
	s_add_u32 s14, s38, 0x0
	s_addc_u32 s15, s39, 0
	global_load_dword v4, v3, s[14:15]
	global_load_dword v5, v3, s[14:15] offset:2048
	s_add_u32 s14, s38, 0x1000
	s_addc_u32 s15, s39, 0
	global_load_dword v6, v3, s[14:15]
	global_load_dword v7, v3, s[14:15] offset:2048
	s_add_u32 s14, s38, 0x2000
	s_addc_u32 s15, s39, 0
	global_load_dword v8, v3, s[14:15]
	global_load_dword v9, v3, s[14:15] offset:2048
	s_add_u32 s14, s38, 0x3000
	s_addc_u32 s15, s39, 0
	global_load_dword v10, v3, s[14:15]
	global_load_dword v11, v3, s[14:15] offset:2048
	s_add_u32 s14, s38, 0x4000
	s_addc_u32 s15, s39, 0
	global_load_dword v12, v3, s[14:15]
	global_load_dword v13, v3, s[14:15] offset:2048
	s_add_u32 s14, s38, 0x5000
	s_addc_u32 s15, s39, 0
	global_load_dword v14, v3, s[14:15]
	global_load_dword v15, v3, s[14:15] offset:2048
	s_add_u32 s14, s38, 0x6000
	s_addc_u32 s15, s39, 0
	global_load_dword v16, v3, s[14:15]
	global_load_dword v17, v3, s[14:15] offset:2048
	s_add_u32 s14, s38, 0x7000
	s_addc_u32 s15, s39, 0
	global_load_dword v18, v3, s[14:15]
	global_load_dword v19, v3, s[14:15] offset:2048
	s_mov_b64 s[14:15], s[42:43]
	global_load_dword v20, v3, s[14:15]
	global_load_dword v21, v3, s[14:15] offset:2048
	s_waitcnt vmcnt(17)
	v_mul_f32_e32 v22, 0xbfb8aa3b, v4
	s_waitcnt vmcnt(16)
	v_mul_f32_e32 v23, 0xbfb8aa3b, v5
	s_waitcnt vmcnt(15)
	v_mul_f32_e32 v24, 0xbfb8aa3b, v6
	s_waitcnt vmcnt(14)
	v_mul_f32_e32 v25, 0xbfb8aa3b, v7
	s_waitcnt vmcnt(13)
	v_mul_f32_e32 v26, 0xbfb8aa3b, v8
	s_waitcnt vmcnt(12)
	v_mul_f32_e32 v27, 0xbfb8aa3b, v9
	s_waitcnt vmcnt(11)
	v_mul_f32_e32 v28, 0xbfb8aa3b, v10
	s_waitcnt vmcnt(10)
	v_mul_f32_e32 v29, 0xbfb8aa3b, v11
	s_waitcnt vmcnt(9)
	v_mul_f32_e32 v30, 0xbfb8aa3b, v12
	s_waitcnt vmcnt(8)
	v_mul_f32_e32 v31, 0xbfb8aa3b, v13
	s_waitcnt vmcnt(7)
	v_mul_f32_e32 v32, 0xbfb8aa3b, v14
	s_waitcnt vmcnt(6)
	v_mul_f32_e32 v33, 0xbfb8aa3b, v15
	s_waitcnt vmcnt(5)
	v_mul_f32_e32 v34, 0xbfb8aa3b, v16
	s_waitcnt vmcnt(4)
	v_mul_f32_e32 v35, 0xbfb8aa3b, v17
	s_waitcnt vmcnt(3)
	v_mul_f32_e32 v36, 0xbfb8aa3b, v18
	s_waitcnt vmcnt(2)
	v_mul_f32_e32 v37, 0xbfb8aa3b, v19
	s_waitcnt vmcnt(1)
	v_mul_f32_e32 v38, 0xbfb8aa3b, v20
	s_waitcnt vmcnt(0)
	v_mul_f32_e32 v39, 0xbfb8aa3b, v21
	v_exp_f32_e32 v22, v22
	v_exp_f32_e32 v23, v23
	v_exp_f32_e32 v24, v24
	v_exp_f32_e32 v25, v25
	v_exp_f32_e32 v26, v26
	v_exp_f32_e32 v27, v27
	v_exp_f32_e32 v28, v28
	v_exp_f32_e32 v29, v29
	v_exp_f32_e32 v30, v30
	v_exp_f32_e32 v31, v31
	v_exp_f32_e32 v32, v32
	v_exp_f32_e32 v33, v33
	v_exp_f32_e32 v34, v34
	v_exp_f32_e32 v35, v35
	v_exp_f32_e32 v36, v36
	v_exp_f32_e32 v37, v37
	v_exp_f32_e32 v38, v38
	v_exp_f32_e32 v39, v39
	v_add_f32_e32 v22, 1.0, v22
	v_add_f32_e32 v23, 1.0, v23
	v_add_f32_e32 v24, 1.0, v24
	v_add_f32_e32 v25, 1.0, v25
	v_add_f32_e32 v26, 1.0, v26
	v_add_f32_e32 v27, 1.0, v27
	v_add_f32_e32 v28, 1.0, v28
	v_add_f32_e32 v29, 1.0, v29
	v_add_f32_e32 v30, 1.0, v30
	v_add_f32_e32 v31, 1.0, v31
	v_add_f32_e32 v32, 1.0, v32
	v_add_f32_e32 v33, 1.0, v33
	v_add_f32_e32 v34, 1.0, v34
	v_add_f32_e32 v35, 1.0, v35
	v_add_f32_e32 v36, 1.0, v36
	v_add_f32_e32 v37, 1.0, v37
	v_add_f32_e32 v38, 1.0, v38
	v_add_f32_e32 v39, 1.0, v39
	v_rcp_f32_e32 v22, v22
	v_rcp_f32_e32 v23, v23
	v_rcp_f32_e32 v24, v24
	v_rcp_f32_e32 v25, v25
	v_rcp_f32_e32 v26, v26
	v_rcp_f32_e32 v27, v27
	v_rcp_f32_e32 v28, v28
	v_rcp_f32_e32 v29, v29
	v_rcp_f32_e32 v30, v30
	v_rcp_f32_e32 v31, v31
	v_rcp_f32_e32 v32, v32
	v_rcp_f32_e32 v33, v33
	v_rcp_f32_e32 v34, v34
	v_rcp_f32_e32 v35, v35
	v_rcp_f32_e32 v36, v36
	v_rcp_f32_e32 v37, v37
	v_rcp_f32_e32 v38, v38
	v_rcp_f32_e32 v39, v39
	v_mul_f32_e32 v4, v4, v22
	v_mul_f32_e32 v5, v5, v23
	v_mul_f32_e32 v6, v6, v24
	v_mul_f32_e32 v7, v7, v25
	v_mul_f32_e32 v8, v8, v26
	v_mul_f32_e32 v9, v9, v27
	v_mul_f32_e32 v10, v10, v28
	v_mul_f32_e32 v11, v11, v29
	v_mul_f32_e32 v12, v12, v30
	v_mul_f32_e32 v13, v13, v31
	v_mul_f32_e32 v14, v14, v32
	v_mul_f32_e32 v15, v15, v33
	v_mul_f32_e32 v16, v16, v34
	v_mul_f32_e32 v17, v17, v35
	v_mul_f32_e32 v18, v18, v36
	v_mul_f32_e32 v19, v19, v37
	v_mul_f32_e32 v20, v20, v38
	v_mul_f32_e32 v21, v21, v39
	ds_write_b32 v3, v4
	ds_write_b32 v3, v5 offset:2048
	ds_write_b32 v3, v6 offset:4096
	ds_write_b32 v3, v7 offset:6144
	ds_write_b32 v3, v8 offset:8192
	ds_write_b32 v3, v9 offset:10240
	ds_write_b32 v3, v10 offset:12288
	ds_write_b32 v3, v11 offset:14336
	ds_write_b32 v3, v12 offset:16384
	ds_write_b32 v3, v13 offset:18432
	ds_write_b32 v3, v14 offset:20480
	ds_write_b32 v3, v15 offset:22528
	ds_write_b32 v3, v16 offset:24576
	ds_write_b32 v3, v17 offset:26624
	ds_write_b32 v3, v18 offset:28672
	ds_write_b32 v3, v19 offset:30720
	ds_write_b32 v3, v20 offset:32768
	ds_write_b32 v3, v21 offset:34816
	s_mul_hi_i32 s8, s22, 0x38e38e39
	s_lshr_b32 s9, s8, 31
	s_ashr_i32 s8, s8, 5
	s_add_i32 s23, s8, s9
	s_mul_i32 s8, s23, 0x90
	s_sub_i32 s8, s22, s8
	s_lshl_b32 s8, s8, 6
	s_ashr_i32 s9, s8, 31
	s_mul_i32 s16, s23, 0x2400000
	s_lshl_b64 s[14:15], s[8:9], 2
	s_mul_hi_i32 s17, s23, 0x2400000
	s_add_u32 s16, s16, s14
	s_addc_u32 s17, s17, s15
	v_mov_b32_e32 v4, 0
	v_lshl_add_u64 v[120:121], v[116:117], 0, s[16:17]
	s_mov_b64 s[16:17], 0
	v_mov_b32_e32 v114, v113
	v_mov_b32_e32 v5, v4
	v_mov_b32_e32 v6, v4
	v_mov_b32_e32 v7, v4
	v_mov_b32_e32 v8, v4
	v_mov_b32_e32 v9, v4
	v_mov_b32_e32 v10, v4
	v_mov_b32_e32 v11, v4
	v_mov_b32_e32 v12, v4
	v_mov_b32_e32 v13, v4
	v_mov_b32_e32 v14, v4
	v_mov_b32_e32 v15, v4
	v_mov_b32_e32 v16, v4
	v_mov_b32_e32 v17, v4
	v_mov_b32_e32 v18, v4
	v_mov_b32_e32 v19, v4
	v_mov_b32_e32 v20, v4
	v_mov_b32_e32 v21, v4
	v_mov_b32_e32 v22, v4
	v_mov_b32_e32 v23, v4
	v_mov_b32_e32 v24, v4
	v_mov_b32_e32 v25, v4
	v_mov_b32_e32 v26, v4
	v_mov_b32_e32 v27, v4
	v_mov_b32_e32 v28, v4
	v_mov_b32_e32 v29, v4
	v_mov_b32_e32 v30, v4
	v_mov_b32_e32 v31, v4
	v_mov_b32_e32 v32, v4
	v_mov_b32_e32 v33, v4
	v_mov_b32_e32 v34, v4
	v_mov_b32_e32 v35, v4
	v_mov_b32_e32 v36, v4
	v_mov_b32_e32 v37, v4
	v_mov_b32_e32 v38, v4
	v_mov_b32_e32 v39, v4
	s_waitcnt lgkmcnt(0)
	s_barrier
; template <bool SILU>
; __device__ __forceinline__ void gemv9_unit(const Ctx& X, const float* c0, int cstride, const float* c8, const float* W, int ldw, int j0, const float* bias, float* out, int ostride) {
;     ...
;     for (int k = 0; k < 32; ++k) { const f32x4 w = *(const f32x4*)(wp + (size_t)k * ldw);
; #pragma unroll
;         for (int r = 0; r < 9; ++r) a[r] += w * sc[r * 1024 + kg * 32 + k]; }
	v_mov_b32_e32 v193, s44
	v_sub_u32_e32 v192, v120, v193
	s_mov_b64 s[16:17], s[44:45]
	global_load_dwordx4 v[126:129], v192, s[16:17]
	s_add_u32 s16, s44, 0x9000
	s_addc_u32 s17, s45, 0
	global_load_dwordx4 v[130:133], v192, s[16:17]
	s_add_u32 s16, s44, 0x12000
	s_addc_u32 s17, s45, 0
	global_load_dwordx4 v[134:137], v192, s[16:17]
	s_add_u32 s16, s44, 0x1b000
	s_addc_u32 s17, s45, 0
	global_load_dwordx4 v[138:141], v192, s[16:17]
	s_add_u32 s16, s44, 0x24000
	s_addc_u32 s17, s45, 0
	global_load_dwordx4 v[142:145], v192, s[16:17]
	s_add_u32 s16, s44, 0x2d000
	s_addc_u32 s17, s45, 0
	global_load_dwordx4 v[146:149], v192, s[16:17]
	s_add_u32 s16, s44, 0x36000
	s_addc_u32 s17, s45, 0
	global_load_dwordx4 v[150:153], v192, s[16:17]
	s_add_u32 s16, s44, 0x3f000
	s_addc_u32 s17, s45, 0
	global_load_dwordx4 v[154:157], v192, s[16:17]
	s_add_u32 s16, s44, 0x48000
	s_addc_u32 s17, s45, 0
	global_load_dwordx4 v[208:211], v192, s[16:17]
	s_add_u32 s16, s44, 0x51000
	s_addc_u32 s17, s45, 0
	global_load_dwordx4 v[212:215], v192, s[16:17]
	s_add_u32 s16, s44, 0x5a000
	s_addc_u32 s17, s45, 0
	global_load_dwordx4 v[216:219], v192, s[16:17]
	s_add_u32 s16, s44, 0x63000
	s_addc_u32 s17, s45, 0
	global_load_dwordx4 v[220:223], v192, s[16:17]
	s_add_u32 s16, s44, 0x6c000
	s_addc_u32 s17, s45, 0
	global_load_dwordx4 v[224:227], v192, s[16:17]
	s_add_u32 s16, s44, 0x75000
	s_addc_u32 s17, s45, 0
	global_load_dwordx4 v[228:231], v192, s[16:17]
	s_add_u32 s16, s44, 0x7e000
	s_addc_u32 s17, s45, 0
	global_load_dwordx4 v[232:235], v192, s[16:17]
	s_add_u32 s16, s44, 0x87000
	s_addc_u32 s17, s45, 0
	global_load_dwordx4 v[236:239], v192, s[16:17]
	ds_read_b128 v[40:43], v114 offset:0
	ds_read_b128 v[44:47], v114 offset:16
	ds_read_b128 v[48:51], v114 offset:4096
	ds_read_b128 v[52:55], v114 offset:4112
	ds_read_b128 v[56:59], v114 offset:8192
	ds_read_b128 v[60:63], v114 offset:8208
	ds_read_b128 v[64:67], v114 offset:12288
	ds_read_b128 v[68:71], v114 offset:12304
	ds_read_b128 v[72:75], v114 offset:16384
	ds_read_b128 v[76:79], v114 offset:16400
	ds_read_b128 v[80:83], v114 offset:20480
	ds_read_b128 v[84:87], v114 offset:20496
	ds_read_b128 v[88:91], v114 offset:24576
	ds_read_b128 v[92:95], v114 offset:24592
	ds_read_b128 v[96:99], v114 offset:28672
	ds_read_b128 v[100:103], v114 offset:28688
	ds_read_b128 v[104:107], v114 offset:32768
	ds_read_b128 v[108:111], v114 offset:32784
	s_waitcnt vmcnt(15) lgkmcnt(0)
	v_pk_fma_f32 v[36:37], v[126:127], v[40:41], v[36:37] op_sel_hi:[1,0,1]
	v_pk_fma_f32 v[38:39], v[128:129], v[40:41], v[38:39] op_sel_hi:[1,0,1]
	v_pk_fma_f32 v[32:33], v[126:127], v[48:49], v[32:33] op_sel_hi:[1,0,1]
	v_pk_fma_f32 v[34:35], v[128:129], v[48:49], v[34:35] op_sel_hi:[1,0,1]
	v_pk_fma_f32 v[28:29], v[126:127], v[56:57], v[28:29] op_sel_hi:[1,0,1]
	v_pk_fma_f32 v[30:31], v[128:129], v[56:57], v[30:31] op_sel_hi:[1,0,1]
	v_pk_fma_f32 v[24:25], v[126:127], v[64:65], v[24:25] op_sel_hi:[1,0,1]
	v_pk_fma_f32 v[26:27], v[128:129], v[64:65], v[26:27] op_sel_hi:[1,0,1]
	v_pk_fma_f32 v[20:21], v[126:127], v[72:73], v[20:21] op_sel_hi:[1,0,1]
	v_pk_fma_f32 v[22:23], v[128:129], v[72:73], v[22:23] op_sel_hi:[1,0,1]
	v_pk_fma_f32 v[16:17], v[126:127], v[80:81], v[16:17] op_sel_hi:[1,0,1]
	v_pk_fma_f32 v[18:19], v[128:129], v[80:81], v[18:19] op_sel_hi:[1,0,1]
	v_pk_fma_f32 v[12:13], v[126:127], v[88:89], v[12:13] op_sel_hi:[1,0,1]
	v_pk_fma_f32 v[14:15], v[128:129], v[88:89], v[14:15] op_sel_hi:[1,0,1]
	v_pk_fma_f32 v[8:9], v[126:127], v[96:97], v[8:9] op_sel_hi:[1,0,1]
	v_pk_fma_f32 v[10:11], v[128:129], v[96:97], v[10:11] op_sel_hi:[1,0,1]
	v_pk_fma_f32 v[4:5], v[126:127], v[104:105], v[4:5] op_sel_hi:[1,0,1]
	v_pk_fma_f32 v[6:7], v[128:129], v[104:105], v[6:7] op_sel_hi:[1,0,1]
	s_waitcnt vmcnt(14)
	v_pk_fma_f32 v[36:37], v[130:131], v[40:41], v[36:37] op_sel:[0,1,0]
	v_pk_fma_f32 v[38:39], v[132:133], v[40:41], v[38:39] op_sel:[0,1,0]
	v_pk_fma_f32 v[32:33], v[130:131], v[48:49], v[32:33] op_sel:[0,1,0]
	v_pk_fma_f32 v[34:35], v[132:133], v[48:49], v[34:35] op_sel:[0,1,0]
	v_pk_fma_f32 v[28:29], v[130:131], v[56:57], v[28:29] op_sel:[0,1,0]
	v_pk_fma_f32 v[30:31], v[132:133], v[56:57], v[30:31] op_sel:[0,1,0]
	v_pk_fma_f32 v[24:25], v[130:131], v[64:65], v[24:25] op_sel:[0,1,0]
	v_pk_fma_f32 v[26:27], v[132:133], v[64:65], v[26:27] op_sel:[0,1,0]
	v_pk_fma_f32 v[20:21], v[130:131], v[72:73], v[20:21] op_sel:[0,1,0]
	v_pk_fma_f32 v[22:23], v[132:133], v[72:73], v[22:23] op_sel:[0,1,0]
	v_pk_fma_f32 v[16:17], v[130:131], v[80:81], v[16:17] op_sel:[0,1,0]
	v_pk_fma_f32 v[18:19], v[132:133], v[80:81], v[18:19] op_sel:[0,1,0]
	v_pk_fma_f32 v[12:13], v[130:131], v[88:89], v[12:13] op_sel:[0,1,0]
	v_pk_fma_f32 v[14:15], v[132:133], v[88:89], v[14:15] op_sel:[0,1,0]
	v_pk_fma_f32 v[8:9], v[130:131], v[96:97], v[8:9] op_sel:[0,1,0]
	v_pk_fma_f32 v[10:11], v[132:133], v[96:97], v[10:11] op_sel:[0,1,0]
	v_pk_fma_f32 v[4:5], v[130:131], v[104:105], v[4:5] op_sel:[0,1,0]
	v_pk_fma_f32 v[6:7], v[132:133], v[104:105], v[6:7] op_sel:[0,1,0]
	s_waitcnt vmcnt(13)
; template <bool SILU>
; __device__ __forceinline__ void gemv9_unit(const Ctx& X, const float* c0, int cstride, const float* c8, const float* W, int ldw, int j0, const float* bias, float* out, int ostride) {
;     ...
;     for (int k = 0; k < 32; ++k) { const f32x4 w = *(const f32x4*)(wp + (size_t)k * ldw);
; #pragma unroll
;         for (int r = 0; r < 9; ++r) a[r] += w * sc[r * 1024 + kg * 32 + k]; }
	v_pk_fma_f32 v[36:37], v[134:135], v[42:43], v[36:37] op_sel_hi:[1,0,1]
	v_pk_fma_f32 v[38:39], v[136:137], v[42:43], v[38:39] op_sel_hi:[1,0,1]
	v_pk_fma_f32 v[32:33], v[134:135], v[50:51], v[32:33] op_sel_hi:[1,0,1]
	v_pk_fma_f32 v[34:35], v[136:137], v[50:51], v[34:35] op_sel_hi:[1,0,1]
	v_pk_fma_f32 v[28:29], v[134:135], v[58:59], v[28:29] op_sel_hi:[1,0,1]
	v_pk_fma_f32 v[30:31], v[136:137], v[58:59], v[30:31] op_sel_hi:[1,0,1]
	v_pk_fma_f32 v[24:25], v[134:135], v[66:67], v[24:25] op_sel_hi:[1,0,1]
	v_pk_fma_f32 v[26:27], v[136:137], v[66:67], v[26:27] op_sel_hi:[1,0,1]
	v_pk_fma_f32 v[20:21], v[134:135], v[74:75], v[20:21] op_sel_hi:[1,0,1]
	v_pk_fma_f32 v[22:23], v[136:137], v[74:75], v[22:23] op_sel_hi:[1,0,1]
	v_pk_fma_f32 v[16:17], v[134:135], v[82:83], v[16:17] op_sel_hi:[1,0,1]
	v_pk_fma_f32 v[18:19], v[136:137], v[82:83], v[18:19] op_sel_hi:[1,0,1]
	v_pk_fma_f32 v[12:13], v[134:135], v[90:91], v[12:13] op_sel_hi:[1,0,1]
	v_pk_fma_f32 v[14:15], v[136:137], v[90:91], v[14:15] op_sel_hi:[1,0,1]
	v_pk_fma_f32 v[8:9], v[134:135], v[98:99], v[8:9] op_sel_hi:[1,0,1]
	v_pk_fma_f32 v[10:11], v[136:137], v[98:99], v[10:11] op_sel_hi:[1,0,1]
	v_pk_fma_f32 v[4:5], v[134:135], v[106:107], v[4:5] op_sel_hi:[1,0,1]
	v_pk_fma_f32 v[6:7], v[136:137], v[106:107], v[6:7] op_sel_hi:[1,0,1]
	s_waitcnt vmcnt(12)
	v_pk_fma_f32 v[36:37], v[138:139], v[42:43], v[36:37] op_sel:[0,1,0]
	v_pk_fma_f32 v[38:39], v[140:141], v[42:43], v[38:39] op_sel:[0,1,0]
	v_pk_fma_f32 v[32:33], v[138:139], v[50:51], v[32:33] op_sel:[0,1,0]
	v_pk_fma_f32 v[34:35], v[140:141], v[50:51], v[34:35] op_sel:[0,1,0]
	v_pk_fma_f32 v[28:29], v[138:139], v[58:59], v[28:29] op_sel:[0,1,0]
	v_pk_fma_f32 v[30:31], v[140:141], v[58:59], v[30:31] op_sel:[0,1,0]
	v_pk_fma_f32 v[24:25], v[138:139], v[66:67], v[24:25] op_sel:[0,1,0]
	v_pk_fma_f32 v[26:27], v[140:141], v[66:67], v[26:27] op_sel:[0,1,0]
	v_pk_fma_f32 v[20:21], v[138:139], v[74:75], v[20:21] op_sel:[0,1,0]
	v_pk_fma_f32 v[22:23], v[140:141], v[74:75], v[22:23] op_sel:[0,1,0]
	v_pk_fma_f32 v[16:17], v[138:139], v[82:83], v[16:17] op_sel:[0,1,0]
	v_pk_fma_f32 v[18:19], v[140:141], v[82:83], v[18:19] op_sel:[0,1,0]
	v_pk_fma_f32 v[12:13], v[138:139], v[90:91], v[12:13] op_sel:[0,1,0]
	v_pk_fma_f32 v[14:15], v[140:141], v[90:91], v[14:15] op_sel:[0,1,0]
	v_pk_fma_f32 v[8:9], v[138:139], v[98:99], v[8:9] op_sel:[0,1,0]
	v_pk_fma_f32 v[10:11], v[140:141], v[98:99], v[10:11] op_sel:[0,1,0]
	v_pk_fma_f32 v[4:5], v[138:139], v[106:107], v[4:5] op_sel:[0,1,0]
	v_pk_fma_f32 v[6:7], v[140:141], v[106:107], v[6:7] op_sel:[0,1,0]
	s_waitcnt vmcnt(11)
	v_pk_fma_f32 v[36:37], v[142:143], v[44:45], v[36:37] op_sel_hi:[1,0,1]
	v_pk_fma_f32 v[38:39], v[144:145], v[44:45], v[38:39] op_sel_hi:[1,0,1]
	v_pk_fma_f32 v[32:33], v[142:143], v[52:53], v[32:33] op_sel_hi:[1,0,1]
	v_pk_fma_f32 v[34:35], v[144:145], v[52:53], v[34:35] op_sel_hi:[1,0,1]
	v_pk_fma_f32 v[28:29], v[142:143], v[60:61], v[28:29] op_sel_hi:[1,0,1]
	v_pk_fma_f32 v[30:31], v[144:145], v[60:61], v[30:31] op_sel_hi:[1,0,1]
	v_pk_fma_f32 v[24:25], v[142:143], v[68:69], v[24:25] op_sel_hi:[1,0,1]
	v_pk_fma_f32 v[26:27], v[144:145], v[68:69], v[26:27] op_sel_hi:[1,0,1]
	v_pk_fma_f32 v[20:21], v[142:143], v[76:77], v[20:21] op_sel_hi:[1,0,1]
	v_pk_fma_f32 v[22:23], v[144:145], v[76:77], v[22:23] op_sel_hi:[1,0,1]
	v_pk_fma_f32 v[16:17], v[142:143], v[84:85], v[16:17] op_sel_hi:[1,0,1]
	v_pk_fma_f32 v[18:19], v[144:145], v[84:85], v[18:19] op_sel_hi:[1,0,1]
	v_pk_fma_f32 v[12:13], v[142:143], v[92:93], v[12:13] op_sel_hi:[1,0,1]
	v_pk_fma_f32 v[14:15], v[144:145], v[92:93], v[14:15] op_sel_hi:[1,0,1]
	v_pk_fma_f32 v[8:9], v[142:143], v[100:101], v[8:9] op_sel_hi:[1,0,1]
	v_pk_fma_f32 v[10:11], v[144:145], v[100:101], v[10:11] op_sel_hi:[1,0,1]
	v_pk_fma_f32 v[4:5], v[142:143], v[108:109], v[4:5] op_sel_hi:[1,0,1]
	v_pk_fma_f32 v[6:7], v[144:145], v[108:109], v[6:7] op_sel_hi:[1,0,1]
	s_waitcnt vmcnt(10)
	v_pk_fma_f32 v[36:37], v[146:147], v[44:45], v[36:37] op_sel:[0,1,0]
	v_pk_fma_f32 v[38:39], v[148:149], v[44:45], v[38:39] op_sel:[0,1,0]
	v_pk_fma_f32 v[32:33], v[146:147], v[52:53], v[32:33] op_sel:[0,1,0]
	v_pk_fma_f32 v[34:35], v[148:149], v[52:53], v[34:35] op_sel:[0,1,0]
	v_pk_fma_f32 v[28:29], v[146:147], v[60:61], v[28:29] op_sel:[0,1,0]
	v_pk_fma_f32 v[30:31], v[148:149], v[60:61], v[30:31] op_sel:[0,1,0]
	v_pk_fma_f32 v[24:25], v[146:147], v[68:69], v[24:25] op_sel:[0,1,0]
	v_pk_fma_f32 v[26:27], v[148:149], v[68:69], v[26:27] op_sel:[0,1,0]
	v_pk_fma_f32 v[20:21], v[146:147], v[76:77], v[20:21] op_sel:[0,1,0]
	v_pk_fma_f32 v[22:23], v[148:149], v[76:77], v[22:23] op_sel:[0,1,0]
	v_pk_fma_f32 v[16:17], v[146:147], v[84:85], v[16:17] op_sel:[0,1,0]
	v_pk_fma_f32 v[18:19], v[148:149], v[84:85], v[18:19] op_sel:[0,1,0]
	v_pk_fma_f32 v[12:13], v[146:147], v[92:93], v[12:13] op_sel:[0,1,0]
	v_pk_fma_f32 v[14:15], v[148:149], v[92:93], v[14:15] op_sel:[0,1,0]
	v_pk_fma_f32 v[8:9], v[146:147], v[100:101], v[8:9] op_sel:[0,1,0]
	v_pk_fma_f32 v[10:11], v[148:149], v[100:101], v[10:11] op_sel:[0,1,0]
	v_pk_fma_f32 v[4:5], v[146:147], v[108:109], v[4:5] op_sel:[0,1,0]
	v_pk_fma_f32 v[6:7], v[148:149], v[108:109], v[6:7] op_sel:[0,1,0]
	s_waitcnt vmcnt(9)
; template <bool SILU>
; __device__ __forceinline__ void gemv9_unit(const Ctx& X, const float* c0, int cstride, const float* c8, const float* W, int ldw, int j0, const float* bias, float* out, int ostride) {
;     ...
;     for (int k = 0; k < 32; ++k) { const f32x4 w = *(const f32x4*)(wp + (size_t)k * ldw);
; #pragma unroll
;         for (int r = 0; r < 9; ++r) a[r] += w * sc[r * 1024 + kg * 32 + k]; }
	v_pk_fma_f32 v[36:37], v[150:151], v[46:47], v[36:37] op_sel_hi:[1,0,1]
	v_pk_fma_f32 v[38:39], v[152:153], v[46:47], v[38:39] op_sel_hi:[1,0,1]
	v_pk_fma_f32 v[32:33], v[150:151], v[54:55], v[32:33] op_sel_hi:[1,0,1]
	v_pk_fma_f32 v[34:35], v[152:153], v[54:55], v[34:35] op_sel_hi:[1,0,1]
	v_pk_fma_f32 v[28:29], v[150:151], v[62:63], v[28:29] op_sel_hi:[1,0,1]
	v_pk_fma_f32 v[30:31], v[152:153], v[62:63], v[30:31] op_sel_hi:[1,0,1]
	v_pk_fma_f32 v[24:25], v[150:151], v[70:71], v[24:25] op_sel_hi:[1,0,1]
	v_pk_fma_f32 v[26:27], v[152:153], v[70:71], v[26:27] op_sel_hi:[1,0,1]
	v_pk_fma_f32 v[20:21], v[150:151], v[78:79], v[20:21] op_sel_hi:[1,0,1]
	v_pk_fma_f32 v[22:23], v[152:153], v[78:79], v[22:23] op_sel_hi:[1,0,1]
	v_pk_fma_f32 v[16:17], v[150:151], v[86:87], v[16:17] op_sel_hi:[1,0,1]
	v_pk_fma_f32 v[18:19], v[152:153], v[86:87], v[18:19] op_sel_hi:[1,0,1]
	v_pk_fma_f32 v[12:13], v[150:151], v[94:95], v[12:13] op_sel_hi:[1,0,1]
	v_pk_fma_f32 v[14:15], v[152:153], v[94:95], v[14:15] op_sel_hi:[1,0,1]
	v_pk_fma_f32 v[8:9], v[150:151], v[102:103], v[8:9] op_sel_hi:[1,0,1]
	v_pk_fma_f32 v[10:11], v[152:153], v[102:103], v[10:11] op_sel_hi:[1,0,1]
	v_pk_fma_f32 v[4:5], v[150:151], v[110:111], v[4:5] op_sel_hi:[1,0,1]
	v_pk_fma_f32 v[6:7], v[152:153], v[110:111], v[6:7] op_sel_hi:[1,0,1]
	s_waitcnt vmcnt(8)
	v_pk_fma_f32 v[36:37], v[154:155], v[46:47], v[36:37] op_sel:[0,1,0]
	v_pk_fma_f32 v[38:39], v[156:157], v[46:47], v[38:39] op_sel:[0,1,0]
	v_pk_fma_f32 v[32:33], v[154:155], v[54:55], v[32:33] op_sel:[0,1,0]
	v_pk_fma_f32 v[34:35], v[156:157], v[54:55], v[34:35] op_sel:[0,1,0]
	v_pk_fma_f32 v[28:29], v[154:155], v[62:63], v[28:29] op_sel:[0,1,0]
	v_pk_fma_f32 v[30:31], v[156:157], v[62:63], v[30:31] op_sel:[0,1,0]
	v_pk_fma_f32 v[24:25], v[154:155], v[70:71], v[24:25] op_sel:[0,1,0]
	v_pk_fma_f32 v[26:27], v[156:157], v[70:71], v[26:27] op_sel:[0,1,0]
	v_pk_fma_f32 v[20:21], v[154:155], v[78:79], v[20:21] op_sel:[0,1,0]
	v_pk_fma_f32 v[22:23], v[156:157], v[78:79], v[22:23] op_sel:[0,1,0]
	v_pk_fma_f32 v[16:17], v[154:155], v[86:87], v[16:17] op_sel:[0,1,0]
	v_pk_fma_f32 v[18:19], v[156:157], v[86:87], v[18:19] op_sel:[0,1,0]
	v_pk_fma_f32 v[12:13], v[154:155], v[94:95], v[12:13] op_sel:[0,1,0]
	v_pk_fma_f32 v[14:15], v[156:157], v[94:95], v[14:15] op_sel:[0,1,0]
	v_pk_fma_f32 v[8:9], v[154:155], v[102:103], v[8:9] op_sel:[0,1,0]
	v_pk_fma_f32 v[10:11], v[156:157], v[102:103], v[10:11] op_sel:[0,1,0]
	v_pk_fma_f32 v[4:5], v[154:155], v[110:111], v[4:5] op_sel:[0,1,0]
	v_pk_fma_f32 v[6:7], v[156:157], v[110:111], v[6:7] op_sel:[0,1,0]
	s_add_u32 s16, s44, 0x90000
	s_addc_u32 s17, s45, 0
	global_load_dwordx4 v[126:129], v192, s[16:17]
	s_add_u32 s16, s44, 0x99000
	s_addc_u32 s17, s45, 0
	global_load_dwordx4 v[130:133], v192, s[16:17]
	s_add_u32 s16, s44, 0xa2000
	s_addc_u32 s17, s45, 0
	global_load_dwordx4 v[134:137], v192, s[16:17]
	s_add_u32 s16, s44, 0xab000
	s_addc_u32 s17, s45, 0
	global_load_dwordx4 v[138:141], v192, s[16:17]
	s_add_u32 s16, s44, 0xb4000
	s_addc_u32 s17, s45, 0
	global_load_dwordx4 v[142:145], v192, s[16:17]
	s_add_u32 s16, s44, 0xbd000
	s_addc_u32 s17, s45, 0
	global_load_dwordx4 v[146:149], v192, s[16:17]
	s_add_u32 s16, s44, 0xc6000
	s_addc_u32 s17, s45, 0
	global_load_dwordx4 v[150:153], v192, s[16:17]
	s_add_u32 s16, s44, 0xcf000
	s_addc_u32 s17, s45, 0
	global_load_dwordx4 v[154:157], v192, s[16:17]
	ds_read_b128 v[40:43], v114 offset:32
	ds_read_b128 v[44:47], v114 offset:48
	ds_read_b128 v[48:51], v114 offset:4128
	ds_read_b128 v[52:55], v114 offset:4144
	ds_read_b128 v[56:59], v114 offset:8224
	ds_read_b128 v[60:63], v114 offset:8240
	ds_read_b128 v[64:67], v114 offset:12320
	ds_read_b128 v[68:71], v114 offset:12336
	ds_read_b128 v[72:75], v114 offset:16416
	ds_read_b128 v[76:79], v114 offset:16432
	ds_read_b128 v[80:83], v114 offset:20512
	ds_read_b128 v[84:87], v114 offset:20528
	ds_read_b128 v[88:91], v114 offset:24608
	ds_read_b128 v[92:95], v114 offset:24624
	ds_read_b128 v[96:99], v114 offset:28704
	ds_read_b128 v[100:103], v114 offset:28720
	ds_read_b128 v[104:107], v114 offset:32800
	ds_read_b128 v[108:111], v114 offset:32816
	s_waitcnt vmcnt(15) lgkmcnt(0)
	v_pk_fma_f32 v[36:37], v[208:209], v[40:41], v[36:37] op_sel_hi:[1,0,1]
	v_pk_fma_f32 v[38:39], v[210:211], v[40:41], v[38:39] op_sel_hi:[1,0,1]
	v_pk_fma_f32 v[32:33], v[208:209], v[48:49], v[32:33] op_sel_hi:[1,0,1]
	v_pk_fma_f32 v[34:35], v[210:211], v[48:49], v[34:35] op_sel_hi:[1,0,1]
	v_pk_fma_f32 v[28:29], v[208:209], v[56:57], v[28:29] op_sel_hi:[1,0,1]
	v_pk_fma_f32 v[30:31], v[210:211], v[56:57], v[30:31] op_sel_hi:[1,0,1]
	v_pk_fma_f32 v[24:25], v[208:209], v[64:65], v[24:25] op_sel_hi:[1,0,1]
	v_pk_fma_f32 v[26:27], v[210:211], v[64:65], v[26:27] op_sel_hi:[1,0,1]
	v_pk_fma_f32 v[20:21], v[208:209], v[72:73], v[20:21] op_sel_hi:[1,0,1]
	v_pk_fma_f32 v[22:23], v[210:211], v[72:73], v[22:23] op_sel_hi:[1,0,1]
	v_pk_fma_f32 v[16:17], v[208:209], v[80:81], v[16:17] op_sel_hi:[1,0,1]
	v_pk_fma_f32 v[18:19], v[210:211], v[80:81], v[18:19] op_sel_hi:[1,0,1]
	v_pk_fma_f32 v[12:13], v[208:209], v[88:89], v[12:13] op_sel_hi:[1,0,1]
	v_pk_fma_f32 v[14:15], v[210:211], v[88:89], v[14:15] op_sel_hi:[1,0,1]
	v_pk_fma_f32 v[8:9], v[208:209], v[96:97], v[8:9] op_sel_hi:[1,0,1]
	v_pk_fma_f32 v[10:11], v[210:211], v[96:97], v[10:11] op_sel_hi:[1,0,1]
	v_pk_fma_f32 v[4:5], v[208:209], v[104:105], v[4:5] op_sel_hi:[1,0,1]
	v_pk_fma_f32 v[6:7], v[210:211], v[104:105], v[6:7] op_sel_hi:[1,0,1]
	s_waitcnt vmcnt(14)
; template <bool SILU>
; __device__ __forceinline__ void gemv9_unit(const Ctx& X, const float* c0, int cstride, const float* c8, const float* W, int ldw, int j0, const float* bias, float* out, int ostride) {
;     ...
;     for (int k = 0; k < 32; ++k) { const f32x4 w = *(const f32x4*)(wp + (size_t)k * ldw);
; #pragma unroll
;         for (int r = 0; r < 9; ++r) a[r] += w * sc[r * 1024 + kg * 32 + k]; }
	v_pk_fma_f32 v[36:37], v[212:213], v[40:41], v[36:37] op_sel:[0,1,0]
	v_pk_fma_f32 v[38:39], v[214:215], v[40:41], v[38:39] op_sel:[0,1,0]
	v_pk_fma_f32 v[32:33], v[212:213], v[48:49], v[32:33] op_sel:[0,1,0]
	v_pk_fma_f32 v[34:35], v[214:215], v[48:49], v[34:35] op_sel:[0,1,0]
	v_pk_fma_f32 v[28:29], v[212:213], v[56:57], v[28:29] op_sel:[0,1,0]
	v_pk_fma_f32 v[30:31], v[214:215], v[56:57], v[30:31] op_sel:[0,1,0]
	v_pk_fma_f32 v[24:25], v[212:213], v[64:65], v[24:25] op_sel:[0,1,0]
	v_pk_fma_f32 v[26:27], v[214:215], v[64:65], v[26:27] op_sel:[0,1,0]
	v_pk_fma_f32 v[20:21], v[212:213], v[72:73], v[20:21] op_sel:[0,1,0]
	v_pk_fma_f32 v[22:23], v[214:215], v[72:73], v[22:23] op_sel:[0,1,0]
	v_pk_fma_f32 v[16:17], v[212:213], v[80:81], v[16:17] op_sel:[0,1,0]
	v_pk_fma_f32 v[18:19], v[214:215], v[80:81], v[18:19] op_sel:[0,1,0]
	v_pk_fma_f32 v[12:13], v[212:213], v[88:89], v[12:13] op_sel:[0,1,0]
	v_pk_fma_f32 v[14:15], v[214:215], v[88:89], v[14:15] op_sel:[0,1,0]
	v_pk_fma_f32 v[8:9], v[212:213], v[96:97], v[8:9] op_sel:[0,1,0]
	v_pk_fma_f32 v[10:11], v[214:215], v[96:97], v[10:11] op_sel:[0,1,0]
	v_pk_fma_f32 v[4:5], v[212:213], v[104:105], v[4:5] op_sel:[0,1,0]
	v_pk_fma_f32 v[6:7], v[214:215], v[104:105], v[6:7] op_sel:[0,1,0]
	s_waitcnt vmcnt(13)
	v_pk_fma_f32 v[36:37], v[216:217], v[42:43], v[36:37] op_sel_hi:[1,0,1]
	v_pk_fma_f32 v[38:39], v[218:219], v[42:43], v[38:39] op_sel_hi:[1,0,1]
	v_pk_fma_f32 v[32:33], v[216:217], v[50:51], v[32:33] op_sel_hi:[1,0,1]
	v_pk_fma_f32 v[34:35], v[218:219], v[50:51], v[34:35] op_sel_hi:[1,0,1]
	v_pk_fma_f32 v[28:29], v[216:217], v[58:59], v[28:29] op_sel_hi:[1,0,1]
	v_pk_fma_f32 v[30:31], v[218:219], v[58:59], v[30:31] op_sel_hi:[1,0,1]
	v_pk_fma_f32 v[24:25], v[216:217], v[66:67], v[24:25] op_sel_hi:[1,0,1]
	v_pk_fma_f32 v[26:27], v[218:219], v[66:67], v[26:27] op_sel_hi:[1,0,1]
	v_pk_fma_f32 v[20:21], v[216:217], v[74:75], v[20:21] op_sel_hi:[1,0,1]
	v_pk_fma_f32 v[22:23], v[218:219], v[74:75], v[22:23] op_sel_hi:[1,0,1]
	v_pk_fma_f32 v[16:17], v[216:217], v[82:83], v[16:17] op_sel_hi:[1,0,1]
	v_pk_fma_f32 v[18:19], v[218:219], v[82:83], v[18:19] op_sel_hi:[1,0,1]
	v_pk_fma_f32 v[12:13], v[216:217], v[90:91], v[12:13] op_sel_hi:[1,0,1]
	v_pk_fma_f32 v[14:15], v[218:219], v[90:91], v[14:15] op_sel_hi:[1,0,1]
	v_pk_fma_f32 v[8:9], v[216:217], v[98:99], v[8:9] op_sel_hi:[1,0,1]
	v_pk_fma_f32 v[10:11], v[218:219], v[98:99], v[10:11] op_sel_hi:[1,0,1]
	v_pk_fma_f32 v[4:5], v[216:217], v[106:107], v[4:5] op_sel_hi:[1,0,1]
	v_pk_fma_f32 v[6:7], v[218:219], v[106:107], v[6:7] op_sel_hi:[1,0,1]
	s_waitcnt vmcnt(12)
	v_pk_fma_f32 v[36:37], v[220:221], v[42:43], v[36:37] op_sel:[0,1,0]
	v_pk_fma_f32 v[38:39], v[222:223], v[42:43], v[38:39] op_sel:[0,1,0]
	v_pk_fma_f32 v[32:33], v[220:221], v[50:51], v[32:33] op_sel:[0,1,0]
	v_pk_fma_f32 v[34:35], v[222:223], v[50:51], v[34:35] op_sel:[0,1,0]
	v_pk_fma_f32 v[28:29], v[220:221], v[58:59], v[28:29] op_sel:[0,1,0]
	v_pk_fma_f32 v[30:31], v[222:223], v[58:59], v[30:31] op_sel:[0,1,0]
	v_pk_fma_f32 v[24:25], v[220:221], v[66:67], v[24:25] op_sel:[0,1,0]
	v_pk_fma_f32 v[26:27], v[222:223], v[66:67], v[26:27] op_sel:[0,1,0]
	v_pk_fma_f32 v[20:21], v[220:221], v[74:75], v[20:21] op_sel:[0,1,0]
	v_pk_fma_f32 v[22:23], v[222:223], v[74:75], v[22:23] op_sel:[0,1,0]
	v_pk_fma_f32 v[16:17], v[220:221], v[82:83], v[16:17] op_sel:[0,1,0]
	v_pk_fma_f32 v[18:19], v[222:223], v[82:83], v[18:19] op_sel:[0,1,0]
	v_pk_fma_f32 v[12:13], v[220:221], v[90:91], v[12:13] op_sel:[0,1,0]
	v_pk_fma_f32 v[14:15], v[222:223], v[90:91], v[14:15] op_sel:[0,1,0]
	v_pk_fma_f32 v[8:9], v[220:221], v[98:99], v[8:9] op_sel:[0,1,0]
	v_pk_fma_f32 v[10:11], v[222:223], v[98:99], v[10:11] op_sel:[0,1,0]
	v_pk_fma_f32 v[4:5], v[220:221], v[106:107], v[4:5] op_sel:[0,1,0]
	v_pk_fma_f32 v[6:7], v[222:223], v[106:107], v[6:7] op_sel:[0,1,0]
	s_waitcnt vmcnt(11)
	v_pk_fma_f32 v[36:37], v[224:225], v[44:45], v[36:37] op_sel_hi:[1,0,1]
	v_pk_fma_f32 v[38:39], v[226:227], v[44:45], v[38:39] op_sel_hi:[1,0,1]
	v_pk_fma_f32 v[32:33], v[224:225], v[52:53], v[32:33] op_sel_hi:[1,0,1]
	v_pk_fma_f32 v[34:35], v[226:227], v[52:53], v[34:35] op_sel_hi:[1,0,1]
	v_pk_fma_f32 v[28:29], v[224:225], v[60:61], v[28:29] op_sel_hi:[1,0,1]
	v_pk_fma_f32 v[30:31], v[226:227], v[60:61], v[30:31] op_sel_hi:[1,0,1]
	v_pk_fma_f32 v[24:25], v[224:225], v[68:69], v[24:25] op_sel_hi:[1,0,1]
	v_pk_fma_f32 v[26:27], v[226:227], v[68:69], v[26:27] op_sel_hi:[1,0,1]
	v_pk_fma_f32 v[20:21], v[224:225], v[76:77], v[20:21] op_sel_hi:[1,0,1]
	v_pk_fma_f32 v[22:23], v[226:227], v[76:77], v[22:23] op_sel_hi:[1,0,1]
	v_pk_fma_f32 v[16:17], v[224:225], v[84:85], v[16:17] op_sel_hi:[1,0,1]
	v_pk_fma_f32 v[18:19], v[226:227], v[84:85], v[18:19] op_sel_hi:[1,0,1]
	v_pk_fma_f32 v[12:13], v[224:225], v[92:93], v[12:13] op_sel_hi:[1,0,1]
	v_pk_fma_f32 v[14:15], v[226:227], v[92:93], v[14:15] op_sel_hi:[1,0,1]
	v_pk_fma_f32 v[8:9], v[224:225], v[100:101], v[8:9] op_sel_hi:[1,0,1]
	v_pk_fma_f32 v[10:11], v[226:227], v[100:101], v[10:11] op_sel_hi:[1,0,1]
	v_pk_fma_f32 v[4:5], v[224:225], v[108:109], v[4:5] op_sel_hi:[1,0,1]
	v_pk_fma_f32 v[6:7], v[226:227], v[108:109], v[6:7] op_sel_hi:[1,0,1]
	s_waitcnt vmcnt(10)
; template <bool SILU>
; __device__ __forceinline__ void gemv9_unit(const Ctx& X, const float* c0, int cstride, const float* c8, const float* W, int ldw, int j0, const float* bias, float* out, int ostride) {
;     ...
;     for (int k = 0; k < 32; ++k) { const f32x4 w = *(const f32x4*)(wp + (size_t)k * ldw);
; #pragma unroll
;         for (int r = 0; r < 9; ++r) a[r] += w * sc[r * 1024 + kg * 32 + k]; }
	v_pk_fma_f32 v[36:37], v[228:229], v[44:45], v[36:37] op_sel:[0,1,0]
	v_pk_fma_f32 v[38:39], v[230:231], v[44:45], v[38:39] op_sel:[0,1,0]
	v_pk_fma_f32 v[32:33], v[228:229], v[52:53], v[32:33] op_sel:[0,1,0]
	v_pk_fma_f32 v[34:35], v[230:231], v[52:53], v[34:35] op_sel:[0,1,0]
	v_pk_fma_f32 v[28:29], v[228:229], v[60:61], v[28:29] op_sel:[0,1,0]
	v_pk_fma_f32 v[30:31], v[230:231], v[60:61], v[30:31] op_sel:[0,1,0]
	v_pk_fma_f32 v[24:25], v[228:229], v[68:69], v[24:25] op_sel:[0,1,0]
	v_pk_fma_f32 v[26:27], v[230:231], v[68:69], v[26:27] op_sel:[0,1,0]
	v_pk_fma_f32 v[20:21], v[228:229], v[76:77], v[20:21] op_sel:[0,1,0]
	v_pk_fma_f32 v[22:23], v[230:231], v[76:77], v[22:23] op_sel:[0,1,0]
	v_pk_fma_f32 v[16:17], v[228:229], v[84:85], v[16:17] op_sel:[0,1,0]
	v_pk_fma_f32 v[18:19], v[230:231], v[84:85], v[18:19] op_sel:[0,1,0]
	v_pk_fma_f32 v[12:13], v[228:229], v[92:93], v[12:13] op_sel:[0,1,0]
	v_pk_fma_f32 v[14:15], v[230:231], v[92:93], v[14:15] op_sel:[0,1,0]
	v_pk_fma_f32 v[8:9], v[228:229], v[100:101], v[8:9] op_sel:[0,1,0]
	v_pk_fma_f32 v[10:11], v[230:231], v[100:101], v[10:11] op_sel:[0,1,0]
	v_pk_fma_f32 v[4:5], v[228:229], v[108:109], v[4:5] op_sel:[0,1,0]
	v_pk_fma_f32 v[6:7], v[230:231], v[108:109], v[6:7] op_sel:[0,1,0]
	s_waitcnt vmcnt(9)
	v_pk_fma_f32 v[36:37], v[232:233], v[46:47], v[36:37] op_sel_hi:[1,0,1]
	v_pk_fma_f32 v[38:39], v[234:235], v[46:47], v[38:39] op_sel_hi:[1,0,1]
	v_pk_fma_f32 v[32:33], v[232:233], v[54:55], v[32:33] op_sel_hi:[1,0,1]
	v_pk_fma_f32 v[34:35], v[234:235], v[54:55], v[34:35] op_sel_hi:[1,0,1]
	v_pk_fma_f32 v[28:29], v[232:233], v[62:63], v[28:29] op_sel_hi:[1,0,1]
	v_pk_fma_f32 v[30:31], v[234:235], v[62:63], v[30:31] op_sel_hi:[1,0,1]
	v_pk_fma_f32 v[24:25], v[232:233], v[70:71], v[24:25] op_sel_hi:[1,0,1]
	v_pk_fma_f32 v[26:27], v[234:235], v[70:71], v[26:27] op_sel_hi:[1,0,1]
	v_pk_fma_f32 v[20:21], v[232:233], v[78:79], v[20:21] op_sel_hi:[1,0,1]
	v_pk_fma_f32 v[22:23], v[234:235], v[78:79], v[22:23] op_sel_hi:[1,0,1]
	v_pk_fma_f32 v[16:17], v[232:233], v[86:87], v[16:17] op_sel_hi:[1,0,1]
	v_pk_fma_f32 v[18:19], v[234:235], v[86:87], v[18:19] op_sel_hi:[1,0,1]
	v_pk_fma_f32 v[12:13], v[232:233], v[94:95], v[12:13] op_sel_hi:[1,0,1]
	v_pk_fma_f32 v[14:15], v[234:235], v[94:95], v[14:15] op_sel_hi:[1,0,1]
	v_pk_fma_f32 v[8:9], v[232:233], v[102:103], v[8:9] op_sel_hi:[1,0,1]
	v_pk_fma_f32 v[10:11], v[234:235], v[102:103], v[10:11] op_sel_hi:[1,0,1]
	v_pk_fma_f32 v[4:5], v[232:233], v[110:111], v[4:5] op_sel_hi:[1,0,1]
	v_pk_fma_f32 v[6:7], v[234:235], v[110:111], v[6:7] op_sel_hi:[1,0,1]
	s_waitcnt vmcnt(8)
	v_pk_fma_f32 v[36:37], v[236:237], v[46:47], v[36:37] op_sel:[0,1,0]
	v_pk_fma_f32 v[38:39], v[238:239], v[46:47], v[38:39] op_sel:[0,1,0]
	v_pk_fma_f32 v[32:33], v[236:237], v[54:55], v[32:33] op_sel:[0,1,0]
	v_pk_fma_f32 v[34:35], v[238:239], v[54:55], v[34:35] op_sel:[0,1,0]
	v_pk_fma_f32 v[28:29], v[236:237], v[62:63], v[28:29] op_sel:[0,1,0]
	v_pk_fma_f32 v[30:31], v[238:239], v[62:63], v[30:31] op_sel:[0,1,0]
	v_pk_fma_f32 v[24:25], v[236:237], v[70:71], v[24:25] op_sel:[0,1,0]
	v_pk_fma_f32 v[26:27], v[238:239], v[70:71], v[26:27] op_sel:[0,1,0]
	v_pk_fma_f32 v[20:21], v[236:237], v[78:79], v[20:21] op_sel:[0,1,0]
	v_pk_fma_f32 v[22:23], v[238:239], v[78:79], v[22:23] op_sel:[0,1,0]
	v_pk_fma_f32 v[16:17], v[236:237], v[86:87], v[16:17] op_sel:[0,1,0]
	v_pk_fma_f32 v[18:19], v[238:239], v[86:87], v[18:19] op_sel:[0,1,0]
	v_pk_fma_f32 v[12:13], v[236:237], v[94:95], v[12:13] op_sel:[0,1,0]
	v_pk_fma_f32 v[14:15], v[238:239], v[94:95], v[14:15] op_sel:[0,1,0]
	v_pk_fma_f32 v[8:9], v[236:237], v[102:103], v[8:9] op_sel:[0,1,0]
	v_pk_fma_f32 v[10:11], v[238:239], v[102:103], v[10:11] op_sel:[0,1,0]
	v_pk_fma_f32 v[4:5], v[236:237], v[110:111], v[4:5] op_sel:[0,1,0]
	v_pk_fma_f32 v[6:7], v[238:239], v[110:111], v[6:7] op_sel:[0,1,0]
	s_add_u32 s16, s44, 0xd8000
	s_addc_u32 s17, s45, 0
	global_load_dwordx4 v[208:211], v192, s[16:17]
	s_add_u32 s16, s44, 0xe1000
	s_addc_u32 s17, s45, 0
	global_load_dwordx4 v[212:215], v192, s[16:17]
	s_add_u32 s16, s44, 0xea000
	s_addc_u32 s17, s45, 0
	global_load_dwordx4 v[216:219], v192, s[16:17]
	s_add_u32 s16, s44, 0xf3000
	s_addc_u32 s17, s45, 0
	global_load_dwordx4 v[220:223], v192, s[16:17]
	s_add_u32 s16, s44, 0xfc000
	s_addc_u32 s17, s45, 0
	global_load_dwordx4 v[224:227], v192, s[16:17]
	s_add_u32 s16, s44, 0x105000
	s_addc_u32 s17, s45, 0
	global_load_dwordx4 v[228:231], v192, s[16:17]
	s_add_u32 s16, s44, 0x10e000
	s_addc_u32 s17, s45, 0
	global_load_dwordx4 v[232:235], v192, s[16:17]
	s_add_u32 s16, s44, 0x117000
	s_addc_u32 s17, s45, 0
	global_load_dwordx4 v[236:239], v192, s[16:17]
	ds_read_b128 v[40:43], v114 offset:64
	ds_read_b128 v[44:47], v114 offset:80
	ds_read_b128 v[48:51], v114 offset:4160
	ds_read_b128 v[52:55], v114 offset:4176
	ds_read_b128 v[56:59], v114 offset:8256
	ds_read_b128 v[60:63], v114 offset:8272
	ds_read_b128 v[64:67], v114 offset:12352
	ds_read_b128 v[68:71], v114 offset:12368
	ds_read_b128 v[72:75], v114 offset:16448
	ds_read_b128 v[76:79], v114 offset:16464
	ds_read_b128 v[80:83], v114 offset:20544
	ds_read_b128 v[84:87], v114 offset:20560
	ds_read_b128 v[88:91], v114 offset:24640
	ds_read_b128 v[92:95], v114 offset:24656
	ds_read_b128 v[96:99], v114 offset:28736
	ds_read_b128 v[100:103], v114 offset:28752
	ds_read_b128 v[104:107], v114 offset:32832
	ds_read_b128 v[108:111], v114 offset:32848
	s_waitcnt vmcnt(15) lgkmcnt(0)
; template <bool SILU>
; __device__ __forceinline__ void gemv9_unit(const Ctx& X, const float* c0, int cstride, const float* c8, const float* W, int ldw, int j0, const float* bias, float* out, int ostride) {
;     ...
;     for (int k = 0; k < 32; ++k) { const f32x4 w = *(const f32x4*)(wp + (size_t)k * ldw);
; #pragma unroll
;         for (int r = 0; r < 9; ++r) a[r] += w * sc[r * 1024 + kg * 32 + k]; }
	v_pk_fma_f32 v[36:37], v[126:127], v[40:41], v[36:37] op_sel_hi:[1,0,1]
	v_pk_fma_f32 v[38:39], v[128:129], v[40:41], v[38:39] op_sel_hi:[1,0,1]
	v_pk_fma_f32 v[32:33], v[126:127], v[48:49], v[32:33] op_sel_hi:[1,0,1]
	v_pk_fma_f32 v[34:35], v[128:129], v[48:49], v[34:35] op_sel_hi:[1,0,1]
	v_pk_fma_f32 v[28:29], v[126:127], v[56:57], v[28:29] op_sel_hi:[1,0,1]
	v_pk_fma_f32 v[30:31], v[128:129], v[56:57], v[30:31] op_sel_hi:[1,0,1]
	v_pk_fma_f32 v[24:25], v[126:127], v[64:65], v[24:25] op_sel_hi:[1,0,1]
	v_pk_fma_f32 v[26:27], v[128:129], v[64:65], v[26:27] op_sel_hi:[1,0,1]
	v_pk_fma_f32 v[20:21], v[126:127], v[72:73], v[20:21] op_sel_hi:[1,0,1]
	v_pk_fma_f32 v[22:23], v[128:129], v[72:73], v[22:23] op_sel_hi:[1,0,1]
	v_pk_fma_f32 v[16:17], v[126:127], v[80:81], v[16:17] op_sel_hi:[1,0,1]
	v_pk_fma_f32 v[18:19], v[128:129], v[80:81], v[18:19] op_sel_hi:[1,0,1]
	v_pk_fma_f32 v[12:13], v[126:127], v[88:89], v[12:13] op_sel_hi:[1,0,1]
	v_pk_fma_f32 v[14:15], v[128:129], v[88:89], v[14:15] op_sel_hi:[1,0,1]
	v_pk_fma_f32 v[8:9], v[126:127], v[96:97], v[8:9] op_sel_hi:[1,0,1]
	v_pk_fma_f32 v[10:11], v[128:129], v[96:97], v[10:11] op_sel_hi:[1,0,1]
	v_pk_fma_f32 v[4:5], v[126:127], v[104:105], v[4:5] op_sel_hi:[1,0,1]
	v_pk_fma_f32 v[6:7], v[128:129], v[104:105], v[6:7] op_sel_hi:[1,0,1]
	s_waitcnt vmcnt(14)
	v_pk_fma_f32 v[36:37], v[130:131], v[40:41], v[36:37] op_sel:[0,1,0]
	v_pk_fma_f32 v[38:39], v[132:133], v[40:41], v[38:39] op_sel:[0,1,0]
	v_pk_fma_f32 v[32:33], v[130:131], v[48:49], v[32:33] op_sel:[0,1,0]
	v_pk_fma_f32 v[34:35], v[132:133], v[48:49], v[34:35] op_sel:[0,1,0]
	v_pk_fma_f32 v[28:29], v[130:131], v[56:57], v[28:29] op_sel:[0,1,0]
	v_pk_fma_f32 v[30:31], v[132:133], v[56:57], v[30:31] op_sel:[0,1,0]
	v_pk_fma_f32 v[24:25], v[130:131], v[64:65], v[24:25] op_sel:[0,1,0]
	v_pk_fma_f32 v[26:27], v[132:133], v[64:65], v[26:27] op_sel:[0,1,0]
	v_pk_fma_f32 v[20:21], v[130:131], v[72:73], v[20:21] op_sel:[0,1,0]
	v_pk_fma_f32 v[22:23], v[132:133], v[72:73], v[22:23] op_sel:[0,1,0]
	v_pk_fma_f32 v[16:17], v[130:131], v[80:81], v[16:17] op_sel:[0,1,0]
	v_pk_fma_f32 v[18:19], v[132:133], v[80:81], v[18:19] op_sel:[0,1,0]
	v_pk_fma_f32 v[12:13], v[130:131], v[88:89], v[12:13] op_sel:[0,1,0]
	v_pk_fma_f32 v[14:15], v[132:133], v[88:89], v[14:15] op_sel:[0,1,0]
	v_pk_fma_f32 v[8:9], v[130:131], v[96:97], v[8:9] op_sel:[0,1,0]
	v_pk_fma_f32 v[10:11], v[132:133], v[96:97], v[10:11] op_sel:[0,1,0]
	v_pk_fma_f32 v[4:5], v[130:131], v[104:105], v[4:5] op_sel:[0,1,0]
	v_pk_fma_f32 v[6:7], v[132:133], v[104:105], v[6:7] op_sel:[0,1,0]
	s_waitcnt vmcnt(13)
	v_pk_fma_f32 v[36:37], v[134:135], v[42:43], v[36:37] op_sel_hi:[1,0,1]
	v_pk_fma_f32 v[38:39], v[136:137], v[42:43], v[38:39] op_sel_hi:[1,0,1]
	v_pk_fma_f32 v[32:33], v[134:135], v[50:51], v[32:33] op_sel_hi:[1,0,1]
	v_pk_fma_f32 v[34:35], v[136:137], v[50:51], v[34:35] op_sel_hi:[1,0,1]
	v_pk_fma_f32 v[28:29], v[134:135], v[58:59], v[28:29] op_sel_hi:[1,0,1]
	v_pk_fma_f32 v[30:31], v[136:137], v[58:59], v[30:31] op_sel_hi:[1,0,1]
	v_pk_fma_f32 v[24:25], v[134:135], v[66:67], v[24:25] op_sel_hi:[1,0,1]
	v_pk_fma_f32 v[26:27], v[136:137], v[66:67], v[26:27] op_sel_hi:[1,0,1]
	v_pk_fma_f32 v[20:21], v[134:135], v[74:75], v[20:21] op_sel_hi:[1,0,1]
	v_pk_fma_f32 v[22:23], v[136:137], v[74:75], v[22:23] op_sel_hi:[1,0,1]
	v_pk_fma_f32 v[16:17], v[134:135], v[82:83], v[16:17] op_sel_hi:[1,0,1]
	v_pk_fma_f32 v[18:19], v[136:137], v[82:83], v[18:19] op_sel_hi:[1,0,1]
	v_pk_fma_f32 v[12:13], v[134:135], v[90:91], v[12:13] op_sel_hi:[1,0,1]
	v_pk_fma_f32 v[14:15], v[136:137], v[90:91], v[14:15] op_sel_hi:[1,0,1]
	v_pk_fma_f32 v[8:9], v[134:135], v[98:99], v[8:9] op_sel_hi:[1,0,1]
	v_pk_fma_f32 v[10:11], v[136:137], v[98:99], v[10:11] op_sel_hi:[1,0,1]
	v_pk_fma_f32 v[4:5], v[134:135], v[106:107], v[4:5] op_sel_hi:[1,0,1]
	v_pk_fma_f32 v[6:7], v[136:137], v[106:107], v[6:7] op_sel_hi:[1,0,1]
	s_waitcnt vmcnt(12)
	v_pk_fma_f32 v[36:37], v[138:139], v[42:43], v[36:37] op_sel:[0,1,0]
	v_pk_fma_f32 v[38:39], v[140:141], v[42:43], v[38:39] op_sel:[0,1,0]
	v_pk_fma_f32 v[32:33], v[138:139], v[50:51], v[32:33] op_sel:[0,1,0]
	v_pk_fma_f32 v[34:35], v[140:141], v[50:51], v[34:35] op_sel:[0,1,0]
	v_pk_fma_f32 v[28:29], v[138:139], v[58:59], v[28:29] op_sel:[0,1,0]
	v_pk_fma_f32 v[30:31], v[140:141], v[58:59], v[30:31] op_sel:[0,1,0]
	v_pk_fma_f32 v[24:25], v[138:139], v[66:67], v[24:25] op_sel:[0,1,0]
	v_pk_fma_f32 v[26:27], v[140:141], v[66:67], v[26:27] op_sel:[0,1,0]
	v_pk_fma_f32 v[20:21], v[138:139], v[74:75], v[20:21] op_sel:[0,1,0]
	v_pk_fma_f32 v[22:23], v[140:141], v[74:75], v[22:23] op_sel:[0,1,0]
	v_pk_fma_f32 v[16:17], v[138:139], v[82:83], v[16:17] op_sel:[0,1,0]
	v_pk_fma_f32 v[18:19], v[140:141], v[82:83], v[18:19] op_sel:[0,1,0]
	v_pk_fma_f32 v[12:13], v[138:139], v[90:91], v[12:13] op_sel:[0,1,0]
	v_pk_fma_f32 v[14:15], v[140:141], v[90:91], v[14:15] op_sel:[0,1,0]
	v_pk_fma_f32 v[8:9], v[138:139], v[98:99], v[8:9] op_sel:[0,1,0]
	v_pk_fma_f32 v[10:11], v[140:141], v[98:99], v[10:11] op_sel:[0,1,0]
	v_pk_fma_f32 v[4:5], v[138:139], v[106:107], v[4:5] op_sel:[0,1,0]
	v_pk_fma_f32 v[6:7], v[140:141], v[106:107], v[6:7] op_sel:[0,1,0]
	s_waitcnt vmcnt(11)
; template <bool SILU>
; __device__ __forceinline__ void gemv9_unit(const Ctx& X, const float* c0, int cstride, const float* c8, const float* W, int ldw, int j0, const float* bias, float* out, int ostride) {
;     ...
;     for (int k = 0; k < 32; ++k) { const f32x4 w = *(const f32x4*)(wp + (size_t)k * ldw);
; #pragma unroll
;         for (int r = 0; r < 9; ++r) a[r] += w * sc[r * 1024 + kg * 32 + k]; }
	v_pk_fma_f32 v[36:37], v[142:143], v[44:45], v[36:37] op_sel_hi:[1,0,1]
	v_pk_fma_f32 v[38:39], v[144:145], v[44:45], v[38:39] op_sel_hi:[1,0,1]
	v_pk_fma_f32 v[32:33], v[142:143], v[52:53], v[32:33] op_sel_hi:[1,0,1]
	v_pk_fma_f32 v[34:35], v[144:145], v[52:53], v[34:35] op_sel_hi:[1,0,1]
	v_pk_fma_f32 v[28:29], v[142:143], v[60:61], v[28:29] op_sel_hi:[1,0,1]
	v_pk_fma_f32 v[30:31], v[144:145], v[60:61], v[30:31] op_sel_hi:[1,0,1]
	v_pk_fma_f32 v[24:25], v[142:143], v[68:69], v[24:25] op_sel_hi:[1,0,1]
	v_pk_fma_f32 v[26:27], v[144:145], v[68:69], v[26:27] op_sel_hi:[1,0,1]
	v_pk_fma_f32 v[20:21], v[142:143], v[76:77], v[20:21] op_sel_hi:[1,0,1]
	v_pk_fma_f32 v[22:23], v[144:145], v[76:77], v[22:23] op_sel_hi:[1,0,1]
	v_pk_fma_f32 v[16:17], v[142:143], v[84:85], v[16:17] op_sel_hi:[1,0,1]
	v_pk_fma_f32 v[18:19], v[144:145], v[84:85], v[18:19] op_sel_hi:[1,0,1]
	v_pk_fma_f32 v[12:13], v[142:143], v[92:93], v[12:13] op_sel_hi:[1,0,1]
	v_pk_fma_f32 v[14:15], v[144:145], v[92:93], v[14:15] op_sel_hi:[1,0,1]
	v_pk_fma_f32 v[8:9], v[142:143], v[100:101], v[8:9] op_sel_hi:[1,0,1]
	v_pk_fma_f32 v[10:11], v[144:145], v[100:101], v[10:11] op_sel_hi:[1,0,1]
	v_pk_fma_f32 v[4:5], v[142:143], v[108:109], v[4:5] op_sel_hi:[1,0,1]
	v_pk_fma_f32 v[6:7], v[144:145], v[108:109], v[6:7] op_sel_hi:[1,0,1]
	s_waitcnt vmcnt(10)
	v_pk_fma_f32 v[36:37], v[146:147], v[44:45], v[36:37] op_sel:[0,1,0]
	v_pk_fma_f32 v[38:39], v[148:149], v[44:45], v[38:39] op_sel:[0,1,0]
	v_pk_fma_f32 v[32:33], v[146:147], v[52:53], v[32:33] op_sel:[0,1,0]
	v_pk_fma_f32 v[34:35], v[148:149], v[52:53], v[34:35] op_sel:[0,1,0]
	v_pk_fma_f32 v[28:29], v[146:147], v[60:61], v[28:29] op_sel:[0,1,0]
	v_pk_fma_f32 v[30:31], v[148:149], v[60:61], v[30:31] op_sel:[0,1,0]
	v_pk_fma_f32 v[24:25], v[146:147], v[68:69], v[24:25] op_sel:[0,1,0]
	v_pk_fma_f32 v[26:27], v[148:149], v[68:69], v[26:27] op_sel:[0,1,0]
	v_pk_fma_f32 v[20:21], v[146:147], v[76:77], v[20:21] op_sel:[0,1,0]
	v_pk_fma_f32 v[22:23], v[148:149], v[76:77], v[22:23] op_sel:[0,1,0]
	v_pk_fma_f32 v[16:17], v[146:147], v[84:85], v[16:17] op_sel:[0,1,0]
	v_pk_fma_f32 v[18:19], v[148:149], v[84:85], v[18:19] op_sel:[0,1,0]
	v_pk_fma_f32 v[12:13], v[146:147], v[92:93], v[12:13] op_sel:[0,1,0]
	v_pk_fma_f32 v[14:15], v[148:149], v[92:93], v[14:15] op_sel:[0,1,0]
	v_pk_fma_f32 v[8:9], v[146:147], v[100:101], v[8:9] op_sel:[0,1,0]
	v_pk_fma_f32 v[10:11], v[148:149], v[100:101], v[10:11] op_sel:[0,1,0]
	v_pk_fma_f32 v[4:5], v[146:147], v[108:109], v[4:5] op_sel:[0,1,0]
	v_pk_fma_f32 v[6:7], v[148:149], v[108:109], v[6:7] op_sel:[0,1,0]
	s_waitcnt vmcnt(9)
	v_pk_fma_f32 v[36:37], v[150:151], v[46:47], v[36:37] op_sel_hi:[1,0,1]
	v_pk_fma_f32 v[38:39], v[152:153], v[46:47], v[38:39] op_sel_hi:[1,0,1]
	v_pk_fma_f32 v[32:33], v[150:151], v[54:55], v[32:33] op_sel_hi:[1,0,1]
	v_pk_fma_f32 v[34:35], v[152:153], v[54:55], v[34:35] op_sel_hi:[1,0,1]
	v_pk_fma_f32 v[28:29], v[150:151], v[62:63], v[28:29] op_sel_hi:[1,0,1]
	v_pk_fma_f32 v[30:31], v[152:153], v[62:63], v[30:31] op_sel_hi:[1,0,1]
	v_pk_fma_f32 v[24:25], v[150:151], v[70:71], v[24:25] op_sel_hi:[1,0,1]
	v_pk_fma_f32 v[26:27], v[152:153], v[70:71], v[26:27] op_sel_hi:[1,0,1]
	v_pk_fma_f32 v[20:21], v[150:151], v[78:79], v[20:21] op_sel_hi:[1,0,1]
	v_pk_fma_f32 v[22:23], v[152:153], v[78:79], v[22:23] op_sel_hi:[1,0,1]
	v_pk_fma_f32 v[16:17], v[150:151], v[86:87], v[16:17] op_sel_hi:[1,0,1]
	v_pk_fma_f32 v[18:19], v[152:153], v[86:87], v[18:19] op_sel_hi:[1,0,1]
	v_pk_fma_f32 v[12:13], v[150:151], v[94:95], v[12:13] op_sel_hi:[1,0,1]
	v_pk_fma_f32 v[14:15], v[152:153], v[94:95], v[14:15] op_sel_hi:[1,0,1]
	v_pk_fma_f32 v[8:9], v[150:151], v[102:103], v[8:9] op_sel_hi:[1,0,1]
	v_pk_fma_f32 v[10:11], v[152:153], v[102:103], v[10:11] op_sel_hi:[1,0,1]
	v_pk_fma_f32 v[4:5], v[150:151], v[110:111], v[4:5] op_sel_hi:[1,0,1]
	v_pk_fma_f32 v[6:7], v[152:153], v[110:111], v[6:7] op_sel_hi:[1,0,1]
	s_waitcnt vmcnt(8)
	v_pk_fma_f32 v[36:37], v[154:155], v[46:47], v[36:37] op_sel:[0,1,0]
	v_pk_fma_f32 v[38:39], v[156:157], v[46:47], v[38:39] op_sel:[0,1,0]
	v_pk_fma_f32 v[32:33], v[154:155], v[54:55], v[32:33] op_sel:[0,1,0]
	v_pk_fma_f32 v[34:35], v[156:157], v[54:55], v[34:35] op_sel:[0,1,0]
	v_pk_fma_f32 v[28:29], v[154:155], v[62:63], v[28:29] op_sel:[0,1,0]
	v_pk_fma_f32 v[30:31], v[156:157], v[62:63], v[30:31] op_sel:[0,1,0]
	v_pk_fma_f32 v[24:25], v[154:155], v[70:71], v[24:25] op_sel:[0,1,0]
	v_pk_fma_f32 v[26:27], v[156:157], v[70:71], v[26:27] op_sel:[0,1,0]
	v_pk_fma_f32 v[20:21], v[154:155], v[78:79], v[20:21] op_sel:[0,1,0]
	v_pk_fma_f32 v[22:23], v[156:157], v[78:79], v[22:23] op_sel:[0,1,0]
	v_pk_fma_f32 v[16:17], v[154:155], v[86:87], v[16:17] op_sel:[0,1,0]
	v_pk_fma_f32 v[18:19], v[156:157], v[86:87], v[18:19] op_sel:[0,1,0]
	v_pk_fma_f32 v[12:13], v[154:155], v[94:95], v[12:13] op_sel:[0,1,0]
	v_pk_fma_f32 v[14:15], v[156:157], v[94:95], v[14:15] op_sel:[0,1,0]
	v_pk_fma_f32 v[8:9], v[154:155], v[102:103], v[8:9] op_sel:[0,1,0]
	v_pk_fma_f32 v[10:11], v[156:157], v[102:103], v[10:11] op_sel:[0,1,0]
	v_pk_fma_f32 v[4:5], v[154:155], v[110:111], v[4:5] op_sel:[0,1,0]
	v_pk_fma_f32 v[6:7], v[156:157], v[110:111], v[6:7] op_sel:[0,1,0]
	ds_read_b128 v[40:43], v114 offset:96
	ds_read_b128 v[44:47], v114 offset:112
	ds_read_b128 v[48:51], v114 offset:4192
	ds_read_b128 v[52:55], v114 offset:4208
	ds_read_b128 v[56:59], v114 offset:8288
	ds_read_b128 v[60:63], v114 offset:8304
	ds_read_b128 v[64:67], v114 offset:12384
	ds_read_b128 v[68:71], v114 offset:12400
	ds_read_b128 v[72:75], v114 offset:16480
	ds_read_b128 v[76:79], v114 offset:16496
	ds_read_b128 v[80:83], v114 offset:20576
	ds_read_b128 v[84:87], v114 offset:20592
	ds_read_b128 v[88:91], v114 offset:24672
	ds_read_b128 v[92:95], v114 offset:24688
	ds_read_b128 v[96:99], v114 offset:28768
	ds_read_b128 v[100:103], v114 offset:28784
	ds_read_b128 v[104:107], v114 offset:32864
	ds_read_b128 v[108:111], v114 offset:32880
	s_waitcnt vmcnt(7) lgkmcnt(0)
; template <bool SILU>
; __device__ __forceinline__ void gemv9_unit(const Ctx& X, const float* c0, int cstride, const float* c8, const float* W, int ldw, int j0, const float* bias, float* out, int ostride) {
;     ...
;     for (int k = 0; k < 32; ++k) { const f32x4 w = *(const f32x4*)(wp + (size_t)k * ldw);
; #pragma unroll
;         for (int r = 0; r < 9; ++r) a[r] += w * sc[r * 1024 + kg * 32 + k]; }
	v_pk_fma_f32 v[36:37], v[208:209], v[40:41], v[36:37] op_sel_hi:[1,0,1]
	v_pk_fma_f32 v[38:39], v[210:211], v[40:41], v[38:39] op_sel_hi:[1,0,1]
	v_pk_fma_f32 v[32:33], v[208:209], v[48:49], v[32:33] op_sel_hi:[1,0,1]
	v_pk_fma_f32 v[34:35], v[210:211], v[48:49], v[34:35] op_sel_hi:[1,0,1]
	v_pk_fma_f32 v[28:29], v[208:209], v[56:57], v[28:29] op_sel_hi:[1,0,1]
	v_pk_fma_f32 v[30:31], v[210:211], v[56:57], v[30:31] op_sel_hi:[1,0,1]
	v_pk_fma_f32 v[24:25], v[208:209], v[64:65], v[24:25] op_sel_hi:[1,0,1]
	v_pk_fma_f32 v[26:27], v[210:211], v[64:65], v[26:27] op_sel_hi:[1,0,1]
	v_pk_fma_f32 v[20:21], v[208:209], v[72:73], v[20:21] op_sel_hi:[1,0,1]
	v_pk_fma_f32 v[22:23], v[210:211], v[72:73], v[22:23] op_sel_hi:[1,0,1]
	v_pk_fma_f32 v[16:17], v[208:209], v[80:81], v[16:17] op_sel_hi:[1,0,1]
	v_pk_fma_f32 v[18:19], v[210:211], v[80:81], v[18:19] op_sel_hi:[1,0,1]
	v_pk_fma_f32 v[12:13], v[208:209], v[88:89], v[12:13] op_sel_hi:[1,0,1]
	v_pk_fma_f32 v[14:15], v[210:211], v[88:89], v[14:15] op_sel_hi:[1,0,1]
	v_pk_fma_f32 v[8:9], v[208:209], v[96:97], v[8:9] op_sel_hi:[1,0,1]
	v_pk_fma_f32 v[10:11], v[210:211], v[96:97], v[10:11] op_sel_hi:[1,0,1]
	v_pk_fma_f32 v[4:5], v[208:209], v[104:105], v[4:5] op_sel_hi:[1,0,1]
	v_pk_fma_f32 v[6:7], v[210:211], v[104:105], v[6:7] op_sel_hi:[1,0,1]
	s_waitcnt vmcnt(6)
	v_pk_fma_f32 v[36:37], v[212:213], v[40:41], v[36:37] op_sel:[0,1,0]
	v_pk_fma_f32 v[38:39], v[214:215], v[40:41], v[38:39] op_sel:[0,1,0]
	v_pk_fma_f32 v[32:33], v[212:213], v[48:49], v[32:33] op_sel:[0,1,0]
	v_pk_fma_f32 v[34:35], v[214:215], v[48:49], v[34:35] op_sel:[0,1,0]
	v_pk_fma_f32 v[28:29], v[212:213], v[56:57], v[28:29] op_sel:[0,1,0]
	v_pk_fma_f32 v[30:31], v[214:215], v[56:57], v[30:31] op_sel:[0,1,0]
	v_pk_fma_f32 v[24:25], v[212:213], v[64:65], v[24:25] op_sel:[0,1,0]
	v_pk_fma_f32 v[26:27], v[214:215], v[64:65], v[26:27] op_sel:[0,1,0]
	v_pk_fma_f32 v[20:21], v[212:213], v[72:73], v[20:21] op_sel:[0,1,0]
	v_pk_fma_f32 v[22:23], v[214:215], v[72:73], v[22:23] op_sel:[0,1,0]
	v_pk_fma_f32 v[16:17], v[212:213], v[80:81], v[16:17] op_sel:[0,1,0]
	v_pk_fma_f32 v[18:19], v[214:215], v[80:81], v[18:19] op_sel:[0,1,0]
	v_pk_fma_f32 v[12:13], v[212:213], v[88:89], v[12:13] op_sel:[0,1,0]
	v_pk_fma_f32 v[14:15], v[214:215], v[88:89], v[14:15] op_sel:[0,1,0]
	v_pk_fma_f32 v[8:9], v[212:213], v[96:97], v[8:9] op_sel:[0,1,0]
	v_pk_fma_f32 v[10:11], v[214:215], v[96:97], v[10:11] op_sel:[0,1,0]
	v_pk_fma_f32 v[4:5], v[212:213], v[104:105], v[4:5] op_sel:[0,1,0]
	v_pk_fma_f32 v[6:7], v[214:215], v[104:105], v[6:7] op_sel:[0,1,0]
	s_waitcnt vmcnt(5)
	v_pk_fma_f32 v[36:37], v[216:217], v[42:43], v[36:37] op_sel_hi:[1,0,1]
	v_pk_fma_f32 v[38:39], v[218:219], v[42:43], v[38:39] op_sel_hi:[1,0,1]
	v_pk_fma_f32 v[32:33], v[216:217], v[50:51], v[32:33] op_sel_hi:[1,0,1]
	v_pk_fma_f32 v[34:35], v[218:219], v[50:51], v[34:35] op_sel_hi:[1,0,1]
	v_pk_fma_f32 v[28:29], v[216:217], v[58:59], v[28:29] op_sel_hi:[1,0,1]
	v_pk_fma_f32 v[30:31], v[218:219], v[58:59], v[30:31] op_sel_hi:[1,0,1]
	v_pk_fma_f32 v[24:25], v[216:217], v[66:67], v[24:25] op_sel_hi:[1,0,1]
	v_pk_fma_f32 v[26:27], v[218:219], v[66:67], v[26:27] op_sel_hi:[1,0,1]
	v_pk_fma_f32 v[20:21], v[216:217], v[74:75], v[20:21] op_sel_hi:[1,0,1]
	v_pk_fma_f32 v[22:23], v[218:219], v[74:75], v[22:23] op_sel_hi:[1,0,1]
	v_pk_fma_f32 v[16:17], v[216:217], v[82:83], v[16:17] op_sel_hi:[1,0,1]
	v_pk_fma_f32 v[18:19], v[218:219], v[82:83], v[18:19] op_sel_hi:[1,0,1]
	v_pk_fma_f32 v[12:13], v[216:217], v[90:91], v[12:13] op_sel_hi:[1,0,1]
	v_pk_fma_f32 v[14:15], v[218:219], v[90:91], v[14:15] op_sel_hi:[1,0,1]
	v_pk_fma_f32 v[8:9], v[216:217], v[98:99], v[8:9] op_sel_hi:[1,0,1]
	v_pk_fma_f32 v[10:11], v[218:219], v[98:99], v[10:11] op_sel_hi:[1,0,1]
	v_pk_fma_f32 v[4:5], v[216:217], v[106:107], v[4:5] op_sel_hi:[1,0,1]
	v_pk_fma_f32 v[6:7], v[218:219], v[106:107], v[6:7] op_sel_hi:[1,0,1]
	s_waitcnt vmcnt(4)
	v_pk_fma_f32 v[36:37], v[220:221], v[42:43], v[36:37] op_sel:[0,1,0]
	v_pk_fma_f32 v[38:39], v[222:223], v[42:43], v[38:39] op_sel:[0,1,0]
	v_pk_fma_f32 v[32:33], v[220:221], v[50:51], v[32:33] op_sel:[0,1,0]
	v_pk_fma_f32 v[34:35], v[222:223], v[50:51], v[34:35] op_sel:[0,1,0]
	v_pk_fma_f32 v[28:29], v[220:221], v[58:59], v[28:29] op_sel:[0,1,0]
	v_pk_fma_f32 v[30:31], v[222:223], v[58:59], v[30:31] op_sel:[0,1,0]
	v_pk_fma_f32 v[24:25], v[220:221], v[66:67], v[24:25] op_sel:[0,1,0]
	v_pk_fma_f32 v[26:27], v[222:223], v[66:67], v[26:27] op_sel:[0,1,0]
	v_pk_fma_f32 v[20:21], v[220:221], v[74:75], v[20:21] op_sel:[0,1,0]
	v_pk_fma_f32 v[22:23], v[222:223], v[74:75], v[22:23] op_sel:[0,1,0]
	v_pk_fma_f32 v[16:17], v[220:221], v[82:83], v[16:17] op_sel:[0,1,0]
	v_pk_fma_f32 v[18:19], v[222:223], v[82:83], v[18:19] op_sel:[0,1,0]
	v_pk_fma_f32 v[12:13], v[220:221], v[90:91], v[12:13] op_sel:[0,1,0]
	v_pk_fma_f32 v[14:15], v[222:223], v[90:91], v[14:15] op_sel:[0,1,0]
	v_pk_fma_f32 v[8:9], v[220:221], v[98:99], v[8:9] op_sel:[0,1,0]
	v_pk_fma_f32 v[10:11], v[222:223], v[98:99], v[10:11] op_sel:[0,1,0]
	v_pk_fma_f32 v[4:5], v[220:221], v[106:107], v[4:5] op_sel:[0,1,0]
	v_pk_fma_f32 v[6:7], v[222:223], v[106:107], v[6:7] op_sel:[0,1,0]
	s_waitcnt vmcnt(3)
; template <bool SILU>
; __device__ __forceinline__ void gemv9_unit(const Ctx& X, const float* c0, int cstride, const float* c8, const float* W, int ldw, int j0, const float* bias, float* out, int ostride) {
;     ...
;     for (int k = 0; k < 32; ++k) { const f32x4 w = *(const f32x4*)(wp + (size_t)k * ldw);
; #pragma unroll
;         for (int r = 0; r < 9; ++r) a[r] += w * sc[r * 1024 + kg * 32 + k]; }
; #pragma unroll
;     for (int r = 0; r < 9; ++r) *(f32x4*)(red + (kg * 9 + r) * 64 + cgi * 4) = a[r];
;     __syncthreads();
;     for (int o = X.tid; o < 576; o += 512) { const int r = o >> 6, j = o & 63; float sm = bias ? bias[j0 + j] : 0.f;
	v_pk_fma_f32 v[36:37], v[224:225], v[44:45], v[36:37] op_sel_hi:[1,0,1]
	v_pk_fma_f32 v[38:39], v[226:227], v[44:45], v[38:39] op_sel_hi:[1,0,1]
	v_pk_fma_f32 v[32:33], v[224:225], v[52:53], v[32:33] op_sel_hi:[1,0,1]
	v_pk_fma_f32 v[34:35], v[226:227], v[52:53], v[34:35] op_sel_hi:[1,0,1]
	v_pk_fma_f32 v[28:29], v[224:225], v[60:61], v[28:29] op_sel_hi:[1,0,1]
	v_pk_fma_f32 v[30:31], v[226:227], v[60:61], v[30:31] op_sel_hi:[1,0,1]
	v_pk_fma_f32 v[24:25], v[224:225], v[68:69], v[24:25] op_sel_hi:[1,0,1]
	v_pk_fma_f32 v[26:27], v[226:227], v[68:69], v[26:27] op_sel_hi:[1,0,1]
	v_pk_fma_f32 v[20:21], v[224:225], v[76:77], v[20:21] op_sel_hi:[1,0,1]
	v_pk_fma_f32 v[22:23], v[226:227], v[76:77], v[22:23] op_sel_hi:[1,0,1]
	v_pk_fma_f32 v[16:17], v[224:225], v[84:85], v[16:17] op_sel_hi:[1,0,1]
	v_pk_fma_f32 v[18:19], v[226:227], v[84:85], v[18:19] op_sel_hi:[1,0,1]
	v_pk_fma_f32 v[12:13], v[224:225], v[92:93], v[12:13] op_sel_hi:[1,0,1]
	v_pk_fma_f32 v[14:15], v[226:227], v[92:93], v[14:15] op_sel_hi:[1,0,1]
	v_pk_fma_f32 v[8:9], v[224:225], v[100:101], v[8:9] op_sel_hi:[1,0,1]
	v_pk_fma_f32 v[10:11], v[226:227], v[100:101], v[10:11] op_sel_hi:[1,0,1]
	v_pk_fma_f32 v[4:5], v[224:225], v[108:109], v[4:5] op_sel_hi:[1,0,1]
	v_pk_fma_f32 v[6:7], v[226:227], v[108:109], v[6:7] op_sel_hi:[1,0,1]
	s_waitcnt vmcnt(2)
	v_pk_fma_f32 v[36:37], v[228:229], v[44:45], v[36:37] op_sel:[0,1,0]
	v_pk_fma_f32 v[38:39], v[230:231], v[44:45], v[38:39] op_sel:[0,1,0]
	v_pk_fma_f32 v[32:33], v[228:229], v[52:53], v[32:33] op_sel:[0,1,0]
	v_pk_fma_f32 v[34:35], v[230:231], v[52:53], v[34:35] op_sel:[0,1,0]
	v_pk_fma_f32 v[28:29], v[228:229], v[60:61], v[28:29] op_sel:[0,1,0]
	v_pk_fma_f32 v[30:31], v[230:231], v[60:61], v[30:31] op_sel:[0,1,0]
	v_pk_fma_f32 v[24:25], v[228:229], v[68:69], v[24:25] op_sel:[0,1,0]
	v_pk_fma_f32 v[26:27], v[230:231], v[68:69], v[26:27] op_sel:[0,1,0]
	v_pk_fma_f32 v[20:21], v[228:229], v[76:77], v[20:21] op_sel:[0,1,0]
	v_pk_fma_f32 v[22:23], v[230:231], v[76:77], v[22:23] op_sel:[0,1,0]
	v_pk_fma_f32 v[16:17], v[228:229], v[84:85], v[16:17] op_sel:[0,1,0]
	v_pk_fma_f32 v[18:19], v[230:231], v[84:85], v[18:19] op_sel:[0,1,0]
	v_pk_fma_f32 v[12:13], v[228:229], v[92:93], v[12:13] op_sel:[0,1,0]
	v_pk_fma_f32 v[14:15], v[230:231], v[92:93], v[14:15] op_sel:[0,1,0]
	v_pk_fma_f32 v[8:9], v[228:229], v[100:101], v[8:9] op_sel:[0,1,0]
	v_pk_fma_f32 v[10:11], v[230:231], v[100:101], v[10:11] op_sel:[0,1,0]
	v_pk_fma_f32 v[4:5], v[228:229], v[108:109], v[4:5] op_sel:[0,1,0]
	v_pk_fma_f32 v[6:7], v[230:231], v[108:109], v[6:7] op_sel:[0,1,0]
	s_waitcnt vmcnt(1)
	v_pk_fma_f32 v[36:37], v[232:233], v[46:47], v[36:37] op_sel_hi:[1,0,1]
	v_pk_fma_f32 v[38:39], v[234:235], v[46:47], v[38:39] op_sel_hi:[1,0,1]
	v_pk_fma_f32 v[32:33], v[232:233], v[54:55], v[32:33] op_sel_hi:[1,0,1]
	v_pk_fma_f32 v[34:35], v[234:235], v[54:55], v[34:35] op_sel_hi:[1,0,1]
	v_pk_fma_f32 v[28:29], v[232:233], v[62:63], v[28:29] op_sel_hi:[1,0,1]
	v_pk_fma_f32 v[30:31], v[234:235], v[62:63], v[30:31] op_sel_hi:[1,0,1]
	v_pk_fma_f32 v[24:25], v[232:233], v[70:71], v[24:25] op_sel_hi:[1,0,1]
	v_pk_fma_f32 v[26:27], v[234:235], v[70:71], v[26:27] op_sel_hi:[1,0,1]
	v_pk_fma_f32 v[20:21], v[232:233], v[78:79], v[20:21] op_sel_hi:[1,0,1]
	v_pk_fma_f32 v[22:23], v[234:235], v[78:79], v[22:23] op_sel_hi:[1,0,1]
	v_pk_fma_f32 v[16:17], v[232:233], v[86:87], v[16:17] op_sel_hi:[1,0,1]
	v_pk_fma_f32 v[18:19], v[234:235], v[86:87], v[18:19] op_sel_hi:[1,0,1]
	v_pk_fma_f32 v[12:13], v[232:233], v[94:95], v[12:13] op_sel_hi:[1,0,1]
	v_pk_fma_f32 v[14:15], v[234:235], v[94:95], v[14:15] op_sel_hi:[1,0,1]
	v_pk_fma_f32 v[8:9], v[232:233], v[102:103], v[8:9] op_sel_hi:[1,0,1]
	v_pk_fma_f32 v[10:11], v[234:235], v[102:103], v[10:11] op_sel_hi:[1,0,1]
	v_pk_fma_f32 v[4:5], v[232:233], v[110:111], v[4:5] op_sel_hi:[1,0,1]
	v_pk_fma_f32 v[6:7], v[234:235], v[110:111], v[6:7] op_sel_hi:[1,0,1]
	s_waitcnt vmcnt(0)
	v_pk_fma_f32 v[36:37], v[236:237], v[46:47], v[36:37] op_sel:[0,1,0]
	v_pk_fma_f32 v[38:39], v[238:239], v[46:47], v[38:39] op_sel:[0,1,0]
	v_pk_fma_f32 v[32:33], v[236:237], v[54:55], v[32:33] op_sel:[0,1,0]
	v_pk_fma_f32 v[34:35], v[238:239], v[54:55], v[34:35] op_sel:[0,1,0]
	v_pk_fma_f32 v[28:29], v[236:237], v[62:63], v[28:29] op_sel:[0,1,0]
	v_pk_fma_f32 v[30:31], v[238:239], v[62:63], v[30:31] op_sel:[0,1,0]
	v_pk_fma_f32 v[24:25], v[236:237], v[70:71], v[24:25] op_sel:[0,1,0]
	v_pk_fma_f32 v[26:27], v[238:239], v[70:71], v[26:27] op_sel:[0,1,0]
	v_pk_fma_f32 v[20:21], v[236:237], v[78:79], v[20:21] op_sel:[0,1,0]
	v_pk_fma_f32 v[22:23], v[238:239], v[78:79], v[22:23] op_sel:[0,1,0]
	v_pk_fma_f32 v[16:17], v[236:237], v[86:87], v[16:17] op_sel:[0,1,0]
	v_pk_fma_f32 v[18:19], v[238:239], v[86:87], v[18:19] op_sel:[0,1,0]
	v_pk_fma_f32 v[12:13], v[236:237], v[94:95], v[12:13] op_sel:[0,1,0]
	v_pk_fma_f32 v[14:15], v[238:239], v[94:95], v[14:15] op_sel:[0,1,0]
	v_pk_fma_f32 v[8:9], v[236:237], v[102:103], v[8:9] op_sel:[0,1,0]
	v_pk_fma_f32 v[10:11], v[238:239], v[102:103], v[10:11] op_sel:[0,1,0]
	v_pk_fma_f32 v[4:5], v[236:237], v[110:111], v[4:5] op_sel:[0,1,0]
	v_pk_fma_f32 v[6:7], v[238:239], v[110:111], v[6:7] op_sel:[0,1,0]
	ds_write_b128 v1, v[36:39] offset:36864
	ds_write_b128 v1, v[32:35] offset:37120
	ds_write_b128 v1, v[28:31] offset:37376
	ds_write_b128 v1, v[24:27] offset:37632
	ds_write_b128 v1, v[20:23] offset:37888
	ds_write_b128 v1, v[16:19] offset:38144
	ds_write_b128 v1, v[12:15] offset:38400
	ds_write_b128 v1, v[8:11] offset:38656
	ds_write_b128 v1, v[4:7] offset:38912
	s_waitcnt lgkmcnt(0)
	s_barrier
	s_and_saveexec_b64 s[16:17], s[6:7]
	s_cbranch_execz .LBB0_35
	s_mul_i32 s24, s23, 0x9000
	s_mul_hi_i32 s9, s23, 0x9000
	s_add_u32 s24, s46, s24
	s_addc_u32 s25, s47, s9
	s_mul_hi_i32 s9, s23, 0x51000
	s_mul_i32 s23, s23, 0x51000
	s_add_u32 s23, s88, s23
	s_addc_u32 s9, s89, s9
	s_add_u32 s14, s23, s14
	v_or_b32_e32 v4, s8, v2
	s_addc_u32 s15, s9, s15
	v_ashrrev_i32_e32 v5, 31, v4
	v_mov_b32_e32 v119, v115
	v_lshl_add_u64 v[4:5], v[4:5], 2, s[24:25]
	v_lshl_add_u64 v[6:7], s[14:15], 0, v[118:119]
	s_mov_b64 s[8:9], 0
	v_mov_b32_e32 v8, v112
